# MFMA order variant: n-major, then m, k-innermost (same-accumulator pairs adjacent) + SwiGLU epilogue rewrite
# speedup vs baseline: 1.0097x; 1.0097x over previous
.LBB0_32:
	s_add_u32 s28, s54, 0xfff80080
	s_addc_u32 s29, s55, -1
	s_add_i32 s30, 0, 0x10000
	s_cmp_eq_u32 s27, 28
	s_cselect_b32 s79, s13, s29
	s_cselect_b32 s78, s16, s28
	s_cselect_b32 s69, s9, s26
	s_cselect_b32 s68, s24, s25
	s_add_i32 s31, 0, 0x14000
	v_add_u32_e32 v142, s30, v184
	v_add_u32_e32 v172, s31, v184
	ds_read_b128 v[130:133], v142
	ds_read_b128 v[134:137], v142 offset:1024
	ds_read_b128 v[138:141], v142 offset:2048
	ds_read_b128 v[142:145], v142 offset:3072
	ds_read_b128 v[146:149], v172
	ds_read_b128 v[150:153], v172 offset:1024
	ds_read_b128 v[154:157], v172 offset:2048
	ds_read_b128 v[172:175], v172 offset:3072
	v_lshl_add_u64 v[212:213], s[54:55], 0, v[166:167]
	s_add_i32 m0, s42, 0xc000
	ds_read_b128 v[176:179], v186
	ds_read_b128 v[180:183], v186 offset:1024
	ds_read_b128 v[188:191], v186 offset:2048
	ds_read_b128 v[192:195], v186 offset:3072
	ds_read_b128 v[196:199], v186 offset:4096
	ds_read_b128 v[200:203], v186 offset:5120
	ds_read_b128 v[204:207], v186 offset:6144
	ds_read_b128 v[208:211], v186 offset:7168
	global_load_lds_dwordx4 v[212:213], off
	v_lshl_add_u64 v[212:213], s[54:55], 0, v[168:169]
	s_add_i32 m0, s42, 0xe000
	s_nop 0
	global_load_lds_dwordx4 v[212:213], off
	s_waitcnt vmcnt(8)
	s_waitcnt lgkmcnt(0)
	s_barrier
	s_setprio 1
	s_waitcnt lgkmcnt(0)
	v_mfma_f32_16x16x32_bf16 v[126:129], v[130:133], v[176:179], v[126:129]
	v_mfma_f32_16x16x32_bf16 v[126:129], v[134:137], v[180:183], v[126:129]
	v_mfma_f32_16x16x32_bf16 v[110:113], v[130:133], v[188:191], v[110:113]
	v_mfma_f32_16x16x32_bf16 v[110:113], v[134:137], v[192:195], v[110:113]
	v_mfma_f32_16x16x32_bf16 v[94:97], v[130:133], v[196:199], v[94:97]
	v_mfma_f32_16x16x32_bf16 v[94:97], v[134:137], v[200:203], v[94:97]
	v_mfma_f32_16x16x32_bf16 v[78:81], v[130:133], v[204:207], v[78:81]
	v_mfma_f32_16x16x32_bf16 v[78:81], v[134:137], v[208:211], v[78:81]
	v_mfma_f32_16x16x32_bf16 v[122:125], v[138:141], v[176:179], v[122:125]
	v_mfma_f32_16x16x32_bf16 v[122:125], v[142:145], v[180:183], v[122:125]
	v_mfma_f32_16x16x32_bf16 v[106:109], v[138:141], v[188:191], v[106:109]
	v_mfma_f32_16x16x32_bf16 v[106:109], v[142:145], v[192:195], v[106:109]
	v_mfma_f32_16x16x32_bf16 v[90:93], v[138:141], v[196:199], v[90:93]
	v_mfma_f32_16x16x32_bf16 v[90:93], v[142:145], v[200:203], v[90:93]
	v_mfma_f32_16x16x32_bf16 v[74:77], v[138:141], v[204:207], v[74:77]
	v_mfma_f32_16x16x32_bf16 v[74:77], v[142:145], v[208:211], v[74:77]
	s_setprio 0
	s_setprio 1
	v_mfma_f32_16x16x32_bf16 v[118:121], v[146:149], v[176:179], v[118:121]
	v_mfma_f32_16x16x32_bf16 v[118:121], v[150:153], v[180:183], v[118:121]
	v_mfma_f32_16x16x32_bf16 v[102:105], v[146:149], v[188:191], v[102:105]
	v_mfma_f32_16x16x32_bf16 v[102:105], v[150:153], v[192:195], v[102:105]
	v_mfma_f32_16x16x32_bf16 v[86:89], v[146:149], v[196:199], v[86:89]
	v_mfma_f32_16x16x32_bf16 v[86:89], v[150:153], v[200:203], v[86:89]
	v_mfma_f32_16x16x32_bf16 v[70:73], v[146:149], v[204:207], v[70:73]
	v_mfma_f32_16x16x32_bf16 v[70:73], v[150:153], v[208:211], v[70:73]
	v_mfma_f32_16x16x32_bf16 v[114:117], v[154:157], v[176:179], v[114:117]
	v_mfma_f32_16x16x32_bf16 v[114:117], v[172:175], v[180:183], v[114:117]
	v_mfma_f32_16x16x32_bf16 v[98:101], v[154:157], v[188:191], v[98:101]
	v_mfma_f32_16x16x32_bf16 v[98:101], v[172:175], v[192:195], v[98:101]
	v_mfma_f32_16x16x32_bf16 v[82:85], v[154:157], v[196:199], v[82:85]
	v_mfma_f32_16x16x32_bf16 v[82:85], v[172:175], v[200:203], v[82:85]
	v_mfma_f32_16x16x32_bf16 v[66:69], v[154:157], v[204:207], v[66:69]
	v_mfma_f32_16x16x32_bf16 v[66:69], v[172:175], v[208:211], v[66:69]
	s_setprio 0
	s_barrier
	s_add_i32 s28, s30, s11
	v_lshl_add_u64 v[212:213], s[68:69], 0, v[160:161]
	s_mov_b32 m0, s28
	ds_read_b128 v[176:179], v186 offset:16384
	ds_read_b128 v[180:183], v186 offset:17408
	ds_read_b128 v[188:191], v186 offset:18432
	ds_read_b128 v[192:195], v186 offset:19456
	ds_read_b128 v[196:199], v186 offset:20480
	ds_read_b128 v[200:203], v186 offset:21504
	ds_read_b128 v[204:207], v186 offset:22528
	ds_read_b128 v[208:211], v186 offset:23552
	global_load_lds_dwordx4 v[212:213], off
	s_add_i32 m0, s28, 0x2000
	s_add_u32 s28, s68, 0x80000
	v_lshl_add_u64 v[232:233], s[68:69], 0, v[164:165]
	s_addc_u32 s29, s69, 0
	s_add_i32 s30, s31, s11
	global_load_lds_dwordx4 v[232:233], off
	v_lshl_add_u64 v[234:235], s[28:29], 0, v[160:161]
	s_mov_b32 m0, s30
	v_lshl_add_u64 v[236:237], s[78:79], 0, v[162:163]
	global_load_lds_dwordx4 v[234:235], off
	v_lshl_add_u64 v[234:235], s[28:29], 0, v[164:165]
	s_add_i32 m0, s30, 0x2000
	s_nop 0
	global_load_lds_dwordx4 v[234:235], off
	v_lshl_add_u64 v[234:235], s[78:79], 0, v[158:159]
	s_mov_b32 m0, s42
	s_nop 0
	global_load_lds_dwordx4 v[234:235], off
	s_mov_b32 m0, s57
	s_nop 0
	global_load_lds_dwordx4 v[236:237], off
	s_waitcnt vmcnt(8)
	s_waitcnt lgkmcnt(0)
	s_barrier
	s_setprio 1
	s_waitcnt lgkmcnt(0)
	v_mfma_f32_16x16x32_bf16 v[62:65], v[130:133], v[176:179], v[62:65]
	v_mfma_f32_16x16x32_bf16 v[62:65], v[134:137], v[180:183], v[62:65]
	v_mfma_f32_16x16x32_bf16 v[46:49], v[130:133], v[188:191], v[46:49]
	v_mfma_f32_16x16x32_bf16 v[46:49], v[134:137], v[192:195], v[46:49]
	v_mfma_f32_16x16x32_bf16 v[30:33], v[130:133], v[196:199], v[30:33]
	v_mfma_f32_16x16x32_bf16 v[30:33], v[134:137], v[200:203], v[30:33]
	v_mfma_f32_16x16x32_bf16 v[14:17], v[130:133], v[204:207], v[14:17]
	v_mfma_f32_16x16x32_bf16 v[14:17], v[134:137], v[208:211], v[14:17]
	v_mfma_f32_16x16x32_bf16 v[58:61], v[138:141], v[176:179], v[58:61]
	v_mfma_f32_16x16x32_bf16 v[58:61], v[142:145], v[180:183], v[58:61]
	v_mfma_f32_16x16x32_bf16 v[42:45], v[138:141], v[188:191], v[42:45]
	v_mfma_f32_16x16x32_bf16 v[42:45], v[142:145], v[192:195], v[42:45]
	v_mfma_f32_16x16x32_bf16 v[26:29], v[138:141], v[196:199], v[26:29]
	v_mfma_f32_16x16x32_bf16 v[26:29], v[142:145], v[200:203], v[26:29]
	v_mfma_f32_16x16x32_bf16 v[10:13], v[138:141], v[204:207], v[10:13]
	v_mfma_f32_16x16x32_bf16 v[10:13], v[142:145], v[208:211], v[10:13]
	s_setprio 0
	s_setprio 1
	v_mfma_f32_16x16x32_bf16 v[54:57], v[146:149], v[176:179], v[54:57]
	v_mfma_f32_16x16x32_bf16 v[54:57], v[150:153], v[180:183], v[54:57]
	v_mfma_f32_16x16x32_bf16 v[38:41], v[146:149], v[188:191], v[38:41]
	v_mfma_f32_16x16x32_bf16 v[38:41], v[150:153], v[192:195], v[38:41]
	v_mfma_f32_16x16x32_bf16 v[22:25], v[146:149], v[196:199], v[22:25]
	v_mfma_f32_16x16x32_bf16 v[22:25], v[150:153], v[200:203], v[22:25]
	v_mfma_f32_16x16x32_bf16 v[6:9], v[146:149], v[204:207], v[6:9]
	v_mfma_f32_16x16x32_bf16 v[6:9], v[150:153], v[208:211], v[6:9]
	v_mfma_f32_16x16x32_bf16 v[50:53], v[154:157], v[176:179], v[50:53]
	v_mfma_f32_16x16x32_bf16 v[50:53], v[172:175], v[180:183], v[50:53]
	v_mfma_f32_16x16x32_bf16 v[34:37], v[154:157], v[188:191], v[34:37]
	v_mfma_f32_16x16x32_bf16 v[34:37], v[172:175], v[192:195], v[34:37]
	v_mfma_f32_16x16x32_bf16 v[18:21], v[154:157], v[196:199], v[18:21]
	v_mfma_f32_16x16x32_bf16 v[18:21], v[172:175], v[200:203], v[18:21]
	v_mfma_f32_16x16x32_bf16 v[2:5], v[154:157], v[204:207], v[2:5]
	v_mfma_f32_16x16x32_bf16 v[2:5], v[172:175], v[208:211], v[2:5]
	s_setprio 0
	s_barrier
	s_add_i32 s30, 0, 0x18000
	s_add_i32 s31, 0, 0x1c000
	v_add_u32_e32 v142, s30, v184
	v_add_u32_e32 v172, s31, v184
	ds_read_b128 v[130:133], v142
	ds_read_b128 v[134:137], v142 offset:1024
	ds_read_b128 v[138:141], v142 offset:2048
	ds_read_b128 v[142:145], v142 offset:3072
	ds_read_b128 v[146:149], v172
	ds_read_b128 v[150:153], v172 offset:1024
	ds_read_b128 v[154:157], v172 offset:2048
	ds_read_b128 v[172:175], v172 offset:3072
	s_add_u32 s28, s78, 0x80000
	s_addc_u32 s29, s79, 0
	s_mov_b32 m0, s67
	v_lshl_add_u64 v[238:239], s[28:29], 0, v[158:159]
	ds_read_b128 v[176:179], v186 offset:32768
	ds_read_b128 v[180:183], v186 offset:33792
	ds_read_b128 v[188:191], v186 offset:34816
	ds_read_b128 v[192:195], v186 offset:35840
	ds_read_b128 v[196:199], v186 offset:36864
	ds_read_b128 v[200:203], v186 offset:37888
	ds_read_b128 v[204:207], v186 offset:38912
	ds_read_b128 v[208:211], v186 offset:39936
	global_load_lds_dwordx4 v[238:239], off
	v_lshl_add_u64 v[238:239], s[28:29], 0, v[162:163]
	s_mov_b32 m0, s72
	s_nop 0
	global_load_lds_dwordx4 v[238:239], off
	s_waitcnt vmcnt(8)
	s_waitcnt lgkmcnt(0)
	s_barrier
	s_setprio 1
	s_waitcnt lgkmcnt(0)
	v_mfma_f32_16x16x32_bf16 v[126:129], v[130:133], v[176:179], v[126:129]
	v_mfma_f32_16x16x32_bf16 v[126:129], v[134:137], v[180:183], v[126:129]
	v_mfma_f32_16x16x32_bf16 v[110:113], v[130:133], v[188:191], v[110:113]
	v_mfma_f32_16x16x32_bf16 v[110:113], v[134:137], v[192:195], v[110:113]
	v_mfma_f32_16x16x32_bf16 v[94:97], v[130:133], v[196:199], v[94:97]
	v_mfma_f32_16x16x32_bf16 v[94:97], v[134:137], v[200:203], v[94:97]
	v_mfma_f32_16x16x32_bf16 v[78:81], v[130:133], v[204:207], v[78:81]
	v_mfma_f32_16x16x32_bf16 v[78:81], v[134:137], v[208:211], v[78:81]
	v_mfma_f32_16x16x32_bf16 v[122:125], v[138:141], v[176:179], v[122:125]
	v_mfma_f32_16x16x32_bf16 v[122:125], v[142:145], v[180:183], v[122:125]
	v_mfma_f32_16x16x32_bf16 v[106:109], v[138:141], v[188:191], v[106:109]
	v_mfma_f32_16x16x32_bf16 v[106:109], v[142:145], v[192:195], v[106:109]
	v_mfma_f32_16x16x32_bf16 v[90:93], v[138:141], v[196:199], v[90:93]
	v_mfma_f32_16x16x32_bf16 v[90:93], v[142:145], v[200:203], v[90:93]
	v_mfma_f32_16x16x32_bf16 v[74:77], v[138:141], v[204:207], v[74:77]
	v_mfma_f32_16x16x32_bf16 v[74:77], v[142:145], v[208:211], v[74:77]
	s_setprio 0
	s_setprio 1
	v_mfma_f32_16x16x32_bf16 v[118:121], v[146:149], v[176:179], v[118:121]
	v_mfma_f32_16x16x32_bf16 v[118:121], v[150:153], v[180:183], v[118:121]
	v_mfma_f32_16x16x32_bf16 v[102:105], v[146:149], v[188:191], v[102:105]
	v_mfma_f32_16x16x32_bf16 v[102:105], v[150:153], v[192:195], v[102:105]
	v_mfma_f32_16x16x32_bf16 v[86:89], v[146:149], v[196:199], v[86:89]
	v_mfma_f32_16x16x32_bf16 v[86:89], v[150:153], v[200:203], v[86:89]
	v_mfma_f32_16x16x32_bf16 v[70:73], v[146:149], v[204:207], v[70:73]
	v_mfma_f32_16x16x32_bf16 v[70:73], v[150:153], v[208:211], v[70:73]
	v_mfma_f32_16x16x32_bf16 v[114:117], v[154:157], v[176:179], v[114:117]
	v_mfma_f32_16x16x32_bf16 v[114:117], v[172:175], v[180:183], v[114:117]
	v_mfma_f32_16x16x32_bf16 v[98:101], v[154:157], v[188:191], v[98:101]
	v_mfma_f32_16x16x32_bf16 v[98:101], v[172:175], v[192:195], v[98:101]
	v_mfma_f32_16x16x32_bf16 v[82:85], v[154:157], v[196:199], v[82:85]
	v_mfma_f32_16x16x32_bf16 v[82:85], v[172:175], v[200:203], v[82:85]
	v_mfma_f32_16x16x32_bf16 v[66:69], v[154:157], v[204:207], v[66:69]
	v_mfma_f32_16x16x32_bf16 v[66:69], v[172:175], v[208:211], v[66:69]
	s_setprio 0
	s_barrier
	s_add_i32 s28, s30, s11
	v_lshl_add_u64 v[212:213], v[212:213], 0, s[62:63]
	s_mov_b32 m0, s28
	ds_read_b128 v[176:179], v186 offset:49152
	ds_read_b128 v[180:183], v186 offset:50176
	ds_read_b128 v[188:191], v186 offset:51200
	ds_read_b128 v[192:195], v186 offset:52224
	ds_read_b128 v[196:199], v186 offset:53248
	ds_read_b128 v[200:203], v186 offset:54272
	ds_read_b128 v[204:207], v186 offset:55296
	ds_read_b128 v[208:211], v186 offset:56320
	global_load_lds_dwordx4 v[212:213], off
	s_add_i32 m0, s28, 0x2000
	s_add_u32 s28, s68, 0x80080
	v_lshl_add_u64 v[212:213], v[232:233], 0, s[62:63]
	s_addc_u32 s29, s69, 0
	s_add_i32 s30, s31, s11
	global_load_lds_dwordx4 v[212:213], off
	v_lshl_add_u64 v[212:213], s[28:29], 0, v[160:161]
	s_mov_b32 m0, s30
	s_nop 0
	global_load_lds_dwordx4 v[212:213], off
	v_lshl_add_u64 v[212:213], s[28:29], 0, v[164:165]
	s_add_i32 m0, s30, 0x2000
	s_nop 0
	global_load_lds_dwordx4 v[212:213], off
	v_lshl_add_u64 v[212:213], v[234:235], 0, s[62:63]
	s_mov_b32 m0, s18
	s_nop 0
	global_load_lds_dwordx4 v[212:213], off
	v_lshl_add_u64 v[212:213], v[236:237], 0, s[62:63]
	s_mov_b32 m0, s19
	s_nop 0
	global_load_lds_dwordx4 v[212:213], off
	s_waitcnt vmcnt(8)
	s_waitcnt lgkmcnt(0)
	s_barrier
	s_setprio 1
	s_waitcnt lgkmcnt(0)
	v_mfma_f32_16x16x32_bf16 v[62:65], v[130:133], v[176:179], v[62:65]
	v_mfma_f32_16x16x32_bf16 v[62:65], v[134:137], v[180:183], v[62:65]
	v_mfma_f32_16x16x32_bf16 v[46:49], v[130:133], v[188:191], v[46:49]
	v_mfma_f32_16x16x32_bf16 v[46:49], v[134:137], v[192:195], v[46:49]
	v_mfma_f32_16x16x32_bf16 v[30:33], v[130:133], v[196:199], v[30:33]
	v_mfma_f32_16x16x32_bf16 v[30:33], v[134:137], v[200:203], v[30:33]
	v_mfma_f32_16x16x32_bf16 v[14:17], v[130:133], v[204:207], v[14:17]
	v_mfma_f32_16x16x32_bf16 v[14:17], v[134:137], v[208:211], v[14:17]
	v_mfma_f32_16x16x32_bf16 v[58:61], v[138:141], v[176:179], v[58:61]
	v_mfma_f32_16x16x32_bf16 v[58:61], v[142:145], v[180:183], v[58:61]
	v_mfma_f32_16x16x32_bf16 v[42:45], v[138:141], v[188:191], v[42:45]
	v_mfma_f32_16x16x32_bf16 v[42:45], v[142:145], v[192:195], v[42:45]
	v_mfma_f32_16x16x32_bf16 v[26:29], v[138:141], v[196:199], v[26:29]
	v_mfma_f32_16x16x32_bf16 v[26:29], v[142:145], v[200:203], v[26:29]
	v_mfma_f32_16x16x32_bf16 v[10:13], v[138:141], v[204:207], v[10:13]
	v_mfma_f32_16x16x32_bf16 v[10:13], v[142:145], v[208:211], v[10:13]
	s_setprio 0
	s_setprio 1
	v_mfma_f32_16x16x32_bf16 v[54:57], v[146:149], v[176:179], v[54:57]
	v_mfma_f32_16x16x32_bf16 v[54:57], v[150:153], v[180:183], v[54:57]
	v_mfma_f32_16x16x32_bf16 v[38:41], v[146:149], v[188:191], v[38:41]
	v_mfma_f32_16x16x32_bf16 v[38:41], v[150:153], v[192:195], v[38:41]
	v_mfma_f32_16x16x32_bf16 v[22:25], v[146:149], v[196:199], v[22:25]
	v_mfma_f32_16x16x32_bf16 v[22:25], v[150:153], v[200:203], v[22:25]
	v_mfma_f32_16x16x32_bf16 v[6:9], v[146:149], v[204:207], v[6:9]
	v_mfma_f32_16x16x32_bf16 v[6:9], v[150:153], v[208:211], v[6:9]
	v_mfma_f32_16x16x32_bf16 v[50:53], v[154:157], v[176:179], v[50:53]
	v_mfma_f32_16x16x32_bf16 v[50:53], v[172:175], v[180:183], v[50:53]
	v_mfma_f32_16x16x32_bf16 v[34:37], v[154:157], v[188:191], v[34:37]
	v_mfma_f32_16x16x32_bf16 v[34:37], v[172:175], v[192:195], v[34:37]
	v_mfma_f32_16x16x32_bf16 v[18:21], v[154:157], v[196:199], v[18:21]
	v_mfma_f32_16x16x32_bf16 v[18:21], v[172:175], v[200:203], v[18:21]
	v_mfma_f32_16x16x32_bf16 v[2:5], v[154:157], v[204:207], v[2:5]
	v_mfma_f32_16x16x32_bf16 v[2:5], v[172:175], v[208:211], v[2:5]
	s_setprio 0
	s_barrier
	s_add_i32 s27, s27, 2
	s_add_u32 s54, s54, 0x100
	s_addc_u32 s55, s55, 0
	s_add_u32 s25, s25, 0x100
	s_addc_u32 s26, s26, 0
	s_cmp_gt_u32 s27, 29
	s_cbranch_scc0 .LBB0_32
	s_and_b64 vcc, exec, s[2:3]
	s_cbranch_vccz .LBB0_35
	s_barrier

.LBB0_132:
	s_add_u32 s23, s48, 0xfff80080
	s_addc_u32 s24, s49, -1
	s_add_i32 s25, 0, 0x10000
	s_cmp_eq_u32 s22, 28
	s_cselect_b32 s69, s3, s24
	s_cselect_b32 s68, s18, s23
	s_cselect_b32 s51, s1, s21
	s_cselect_b32 s50, s19, s20
	s_add_i32 s23, 0, 0x14000
	v_add_u32_e32 v156, s25, v165
	v_add_u32_e32 v169, s23, v165
	ds_read_b128 v[144:147], v156
	ds_read_b128 v[148:151], v156 offset:1024
	ds_read_b128 v[152:155], v156 offset:2048
	ds_read_b128 v[156:159], v156 offset:3072
	ds_read_b128 v[160:163], v169
	ds_read_b128 v[170:173], v169 offset:1024
	ds_read_b128 v[174:177], v169 offset:2048
	ds_read_b128 v[178:181], v169 offset:3072
	v_lshl_add_u64 v[232:233], s[48:49], 0, v[140:141]
	s_add_i32 m0, s45, 0xc000
	ds_read_b128 v[182:185], v168
	ds_read_b128 v[186:189], v168 offset:1024
	ds_read_b128 v[190:193], v168 offset:2048
	ds_read_b128 v[194:197], v168 offset:3072
	ds_read_b128 v[198:201], v168 offset:4096
	ds_read_b128 v[202:205], v168 offset:5120
	ds_read_b128 v[206:209], v168 offset:6144
	ds_read_b128 v[210:213], v168 offset:7168
	global_load_lds_dwordx4 v[232:233], off
	v_lshl_add_u64 v[232:233], s[48:49], 0, v[142:143]
	s_add_i32 m0, s45, 0xe000
	s_nop 0
	global_load_lds_dwordx4 v[232:233], off
	s_waitcnt vmcnt(8)
	s_waitcnt lgkmcnt(0)
	s_barrier
	s_setprio 1
	s_waitcnt lgkmcnt(0)
	v_mfma_f32_16x16x32_bf16 v[126:129], v[144:147], v[182:185], v[126:129]
	v_mfma_f32_16x16x32_bf16 v[126:129], v[148:151], v[186:189], v[126:129]
	v_mfma_f32_16x16x32_bf16 v[110:113], v[144:147], v[190:193], v[110:113]
	v_mfma_f32_16x16x32_bf16 v[110:113], v[148:151], v[194:197], v[110:113]
	v_mfma_f32_16x16x32_bf16 v[102:105], v[144:147], v[198:201], v[102:105]
	v_mfma_f32_16x16x32_bf16 v[102:105], v[148:151], v[202:205], v[102:105]
	v_mfma_f32_16x16x32_bf16 v[86:89], v[144:147], v[206:209], v[86:89]
	v_mfma_f32_16x16x32_bf16 v[86:89], v[148:151], v[210:213], v[86:89]
	v_mfma_f32_16x16x32_bf16 v[122:125], v[152:155], v[182:185], v[122:125]
	v_mfma_f32_16x16x32_bf16 v[122:125], v[156:159], v[186:189], v[122:125]
	v_mfma_f32_16x16x32_bf16 v[106:109], v[152:155], v[190:193], v[106:109]
	v_mfma_f32_16x16x32_bf16 v[106:109], v[156:159], v[194:197], v[106:109]
	v_mfma_f32_16x16x32_bf16 v[94:97], v[152:155], v[198:201], v[94:97]
	v_mfma_f32_16x16x32_bf16 v[94:97], v[156:159], v[202:205], v[94:97]
	v_mfma_f32_16x16x32_bf16 v[78:81], v[152:155], v[206:209], v[78:81]
	v_mfma_f32_16x16x32_bf16 v[78:81], v[156:159], v[210:213], v[78:81]
	s_setprio 0
	s_setprio 1
	v_mfma_f32_16x16x32_bf16 v[118:121], v[160:163], v[182:185], v[118:121]
	v_mfma_f32_16x16x32_bf16 v[118:121], v[170:173], v[186:189], v[118:121]
	v_mfma_f32_16x16x32_bf16 v[98:101], v[160:163], v[190:193], v[98:101]
	v_mfma_f32_16x16x32_bf16 v[98:101], v[170:173], v[194:197], v[98:101]
	v_mfma_f32_16x16x32_bf16 v[82:85], v[160:163], v[198:201], v[82:85]
	v_mfma_f32_16x16x32_bf16 v[82:85], v[170:173], v[202:205], v[82:85]
	v_mfma_f32_16x16x32_bf16 v[70:73], v[160:163], v[206:209], v[70:73]
	v_mfma_f32_16x16x32_bf16 v[70:73], v[170:173], v[210:213], v[70:73]
	v_mfma_f32_16x16x32_bf16 v[114:117], v[174:177], v[182:185], v[114:117]
	v_mfma_f32_16x16x32_bf16 v[114:117], v[178:181], v[186:189], v[114:117]
	v_mfma_f32_16x16x32_bf16 v[90:93], v[174:177], v[190:193], v[90:93]
	v_mfma_f32_16x16x32_bf16 v[90:93], v[178:181], v[194:197], v[90:93]
	v_mfma_f32_16x16x32_bf16 v[74:77], v[174:177], v[198:201], v[74:77]
	v_mfma_f32_16x16x32_bf16 v[74:77], v[178:181], v[202:205], v[74:77]
	v_mfma_f32_16x16x32_bf16 v[66:69], v[174:177], v[206:209], v[66:69]
	v_mfma_f32_16x16x32_bf16 v[66:69], v[178:181], v[210:213], v[66:69]
	s_setprio 0
	s_barrier
	s_add_i32 s24, s25, s16
	v_lshl_add_u64 v[232:233], s[50:51], 0, v[132:133]
	s_mov_b32 m0, s24
	ds_read_b128 v[182:185], v168 offset:16384
	ds_read_b128 v[186:189], v168 offset:17408
	ds_read_b128 v[190:193], v168 offset:18432
	ds_read_b128 v[194:197], v168 offset:19456
	ds_read_b128 v[198:201], v168 offset:20480
	ds_read_b128 v[202:205], v168 offset:21504
	ds_read_b128 v[206:209], v168 offset:22528
	ds_read_b128 v[210:213], v168 offset:23552
	global_load_lds_dwordx4 v[232:233], off
	s_add_i32 m0, s24, 0x2000
	s_add_u32 s24, s50, 0x80000
	v_lshl_add_u64 v[234:235], s[50:51], 0, v[136:137]
	s_addc_u32 s25, s51, 0
	s_add_i32 s23, s23, s16
	global_load_lds_dwordx4 v[234:235], off
	v_lshl_add_u64 v[236:237], s[24:25], 0, v[132:133]
	s_mov_b32 m0, s23
	v_lshl_add_u64 v[238:239], s[68:69], 0, v[134:135]
	global_load_lds_dwordx4 v[236:237], off
	v_lshl_add_u64 v[236:237], s[24:25], 0, v[136:137]
	s_add_i32 m0, s23, 0x2000
	s_nop 0
	global_load_lds_dwordx4 v[236:237], off
	v_lshl_add_u64 v[236:237], s[68:69], 0, v[130:131]
	s_mov_b32 m0, s45
	s_nop 0
	global_load_lds_dwordx4 v[236:237], off
	s_mov_b32 m0, s57
	s_nop 0
	global_load_lds_dwordx4 v[238:239], off
	s_waitcnt vmcnt(8)
	s_waitcnt lgkmcnt(0)
	s_barrier
	s_setprio 1
	s_waitcnt lgkmcnt(0)
	v_mfma_f32_16x16x32_bf16 v[62:65], v[144:147], v[182:185], v[62:65]
	v_mfma_f32_16x16x32_bf16 v[62:65], v[148:151], v[186:189], v[62:65]
	v_mfma_f32_16x16x32_bf16 v[54:57], v[144:147], v[190:193], v[54:57]
	v_mfma_f32_16x16x32_bf16 v[54:57], v[148:151], v[194:197], v[54:57]
	v_mfma_f32_16x16x32_bf16 v[38:41], v[144:147], v[198:201], v[38:41]
	v_mfma_f32_16x16x32_bf16 v[38:41], v[148:151], v[202:205], v[38:41]
	v_mfma_f32_16x16x32_bf16 v[22:25], v[144:147], v[206:209], v[22:25]
	v_mfma_f32_16x16x32_bf16 v[22:25], v[148:151], v[210:213], v[22:25]
	v_mfma_f32_16x16x32_bf16 v[58:61], v[152:155], v[182:185], v[58:61]
	v_mfma_f32_16x16x32_bf16 v[58:61], v[156:159], v[186:189], v[58:61]
	v_mfma_f32_16x16x32_bf16 v[46:49], v[152:155], v[190:193], v[46:49]
	v_mfma_f32_16x16x32_bf16 v[46:49], v[156:159], v[194:197], v[46:49]
	v_mfma_f32_16x16x32_bf16 v[30:33], v[152:155], v[198:201], v[30:33]
	v_mfma_f32_16x16x32_bf16 v[30:33], v[156:159], v[202:205], v[30:33]
	v_mfma_f32_16x16x32_bf16 v[14:17], v[152:155], v[206:209], v[14:17]
	v_mfma_f32_16x16x32_bf16 v[14:17], v[156:159], v[210:213], v[14:17]
	s_setprio 0
	s_setprio 1
	v_mfma_f32_16x16x32_bf16 v[50:53], v[160:163], v[182:185], v[50:53]
	v_mfma_f32_16x16x32_bf16 v[50:53], v[170:173], v[186:189], v[50:53]
	v_mfma_f32_16x16x32_bf16 v[34:37], v[160:163], v[190:193], v[34:37]
	v_mfma_f32_16x16x32_bf16 v[34:37], v[170:173], v[194:197], v[34:37]
	v_mfma_f32_16x16x32_bf16 v[18:21], v[160:163], v[198:201], v[18:21]
	v_mfma_f32_16x16x32_bf16 v[18:21], v[170:173], v[202:205], v[18:21]
	v_mfma_f32_16x16x32_bf16 v[6:9], v[160:163], v[206:209], v[6:9]
	v_mfma_f32_16x16x32_bf16 v[6:9], v[170:173], v[210:213], v[6:9]
	v_mfma_f32_16x16x32_bf16 v[42:45], v[174:177], v[182:185], v[42:45]
	v_mfma_f32_16x16x32_bf16 v[42:45], v[178:181], v[186:189], v[42:45]
	v_mfma_f32_16x16x32_bf16 v[26:29], v[174:177], v[190:193], v[26:29]
	v_mfma_f32_16x16x32_bf16 v[26:29], v[178:181], v[194:197], v[26:29]
	v_mfma_f32_16x16x32_bf16 v[10:13], v[174:177], v[198:201], v[10:13]
	v_mfma_f32_16x16x32_bf16 v[10:13], v[178:181], v[202:205], v[10:13]
	v_mfma_f32_16x16x32_bf16 v[2:5], v[174:177], v[206:209], v[2:5]
	v_mfma_f32_16x16x32_bf16 v[2:5], v[178:181], v[210:213], v[2:5]
	s_setprio 0
	s_barrier
	s_add_i32 s23, 0, 0x18000
	s_add_i32 s26, 0, 0x1c000
	v_add_u32_e32 v156, s23, v165
	v_add_u32_e32 v169, s26, v165
	ds_read_b128 v[144:147], v156
	ds_read_b128 v[148:151], v156 offset:1024
	ds_read_b128 v[152:155], v156 offset:2048
	ds_read_b128 v[156:159], v156 offset:3072
	ds_read_b128 v[160:163], v169
	ds_read_b128 v[170:173], v169 offset:1024
	ds_read_b128 v[174:177], v169 offset:2048
	ds_read_b128 v[178:181], v169 offset:3072
	s_add_u32 s24, s68, 0x80000
	s_addc_u32 s25, s69, 0
	s_mov_b32 m0, s42
	v_lshl_add_u64 v[240:241], s[24:25], 0, v[130:131]
	ds_read_b128 v[182:185], v168 offset:32768
	ds_read_b128 v[186:189], v168 offset:33792
	ds_read_b128 v[190:193], v168 offset:34816
	ds_read_b128 v[194:197], v168 offset:35840
	ds_read_b128 v[198:201], v168 offset:36864
	ds_read_b128 v[202:205], v168 offset:37888
	ds_read_b128 v[206:209], v168 offset:38912
	ds_read_b128 v[210:213], v168 offset:39936
	global_load_lds_dwordx4 v[240:241], off
	v_lshl_add_u64 v[240:241], s[24:25], 0, v[134:135]
	s_mov_b32 m0, s6
	s_nop 0
	global_load_lds_dwordx4 v[240:241], off
	s_waitcnt vmcnt(8)
	s_waitcnt lgkmcnt(0)
	s_barrier
	s_setprio 1
	s_waitcnt lgkmcnt(0)
	v_mfma_f32_16x16x32_bf16 v[126:129], v[144:147], v[182:185], v[126:129]
	v_mfma_f32_16x16x32_bf16 v[126:129], v[148:151], v[186:189], v[126:129]
	v_mfma_f32_16x16x32_bf16 v[110:113], v[144:147], v[190:193], v[110:113]
	v_mfma_f32_16x16x32_bf16 v[110:113], v[148:151], v[194:197], v[110:113]
	v_mfma_f32_16x16x32_bf16 v[102:105], v[144:147], v[198:201], v[102:105]
	v_mfma_f32_16x16x32_bf16 v[102:105], v[148:151], v[202:205], v[102:105]
	v_mfma_f32_16x16x32_bf16 v[86:89], v[144:147], v[206:209], v[86:89]
	v_mfma_f32_16x16x32_bf16 v[86:89], v[148:151], v[210:213], v[86:89]
	v_mfma_f32_16x16x32_bf16 v[122:125], v[152:155], v[182:185], v[122:125]
	v_mfma_f32_16x16x32_bf16 v[122:125], v[156:159], v[186:189], v[122:125]
	v_mfma_f32_16x16x32_bf16 v[106:109], v[152:155], v[190:193], v[106:109]
	v_mfma_f32_16x16x32_bf16 v[106:109], v[156:159], v[194:197], v[106:109]
	v_mfma_f32_16x16x32_bf16 v[94:97], v[152:155], v[198:201], v[94:97]
	v_mfma_f32_16x16x32_bf16 v[94:97], v[156:159], v[202:205], v[94:97]
	v_mfma_f32_16x16x32_bf16 v[78:81], v[152:155], v[206:209], v[78:81]
	v_mfma_f32_16x16x32_bf16 v[78:81], v[156:159], v[210:213], v[78:81]
	s_setprio 0
	s_setprio 1
	v_mfma_f32_16x16x32_bf16 v[118:121], v[160:163], v[182:185], v[118:121]
	v_mfma_f32_16x16x32_bf16 v[118:121], v[170:173], v[186:189], v[118:121]
	v_mfma_f32_16x16x32_bf16 v[98:101], v[160:163], v[190:193], v[98:101]
	v_mfma_f32_16x16x32_bf16 v[98:101], v[170:173], v[194:197], v[98:101]
	v_mfma_f32_16x16x32_bf16 v[82:85], v[160:163], v[198:201], v[82:85]
	v_mfma_f32_16x16x32_bf16 v[82:85], v[170:173], v[202:205], v[82:85]
	v_mfma_f32_16x16x32_bf16 v[70:73], v[160:163], v[206:209], v[70:73]
	v_mfma_f32_16x16x32_bf16 v[70:73], v[170:173], v[210:213], v[70:73]
	v_mfma_f32_16x16x32_bf16 v[114:117], v[174:177], v[182:185], v[114:117]
	v_mfma_f32_16x16x32_bf16 v[114:117], v[178:181], v[186:189], v[114:117]
	v_mfma_f32_16x16x32_bf16 v[90:93], v[174:177], v[190:193], v[90:93]
	v_mfma_f32_16x16x32_bf16 v[90:93], v[178:181], v[194:197], v[90:93]
	v_mfma_f32_16x16x32_bf16 v[74:77], v[174:177], v[198:201], v[74:77]
	v_mfma_f32_16x16x32_bf16 v[74:77], v[178:181], v[202:205], v[74:77]
	v_mfma_f32_16x16x32_bf16 v[66:69], v[174:177], v[206:209], v[66:69]
	v_mfma_f32_16x16x32_bf16 v[66:69], v[178:181], v[210:213], v[66:69]
	s_setprio 0
	s_barrier
	s_add_i32 s23, s23, s16
	v_lshl_add_u64 v[232:233], v[232:233], 0, s[62:63]
	s_mov_b32 m0, s23
	ds_read_b128 v[182:185], v168 offset:49152
	ds_read_b128 v[186:189], v168 offset:50176
	ds_read_b128 v[190:193], v168 offset:51200
	ds_read_b128 v[194:197], v168 offset:52224
	ds_read_b128 v[198:201], v168 offset:53248
	ds_read_b128 v[202:205], v168 offset:54272
	ds_read_b128 v[206:209], v168 offset:55296
	ds_read_b128 v[210:213], v168 offset:56320
	global_load_lds_dwordx4 v[232:233], off
	s_add_i32 m0, s23, 0x2000
	s_add_u32 s24, s50, 0x80080
	v_lshl_add_u64 v[232:233], v[234:235], 0, s[62:63]
	s_addc_u32 s25, s51, 0
	s_add_i32 s23, s26, s16
	global_load_lds_dwordx4 v[232:233], off
	v_lshl_add_u64 v[232:233], s[24:25], 0, v[132:133]
	s_mov_b32 m0, s23
	s_nop 0
	global_load_lds_dwordx4 v[232:233], off
	v_lshl_add_u64 v[232:233], s[24:25], 0, v[136:137]
	s_add_i32 m0, s23, 0x2000
	s_nop 0
	global_load_lds_dwordx4 v[232:233], off
	v_lshl_add_u64 v[232:233], v[236:237], 0, s[62:63]
	s_mov_b32 m0, s76
	s_nop 0
	global_load_lds_dwordx4 v[232:233], off
	v_lshl_add_u64 v[232:233], v[238:239], 0, s[62:63]
	s_mov_b32 m0, s77
	s_nop 0
	global_load_lds_dwordx4 v[232:233], off
	s_waitcnt vmcnt(8)
	s_waitcnt lgkmcnt(0)
	s_barrier
	s_setprio 1
	s_waitcnt lgkmcnt(0)
	v_mfma_f32_16x16x32_bf16 v[62:65], v[144:147], v[182:185], v[62:65]
	v_mfma_f32_16x16x32_bf16 v[62:65], v[148:151], v[186:189], v[62:65]
	v_mfma_f32_16x16x32_bf16 v[54:57], v[144:147], v[190:193], v[54:57]
	v_mfma_f32_16x16x32_bf16 v[54:57], v[148:151], v[194:197], v[54:57]
	v_mfma_f32_16x16x32_bf16 v[38:41], v[144:147], v[198:201], v[38:41]
	v_mfma_f32_16x16x32_bf16 v[38:41], v[148:151], v[202:205], v[38:41]
	v_mfma_f32_16x16x32_bf16 v[22:25], v[144:147], v[206:209], v[22:25]
	v_mfma_f32_16x16x32_bf16 v[22:25], v[148:151], v[210:213], v[22:25]
	v_mfma_f32_16x16x32_bf16 v[58:61], v[152:155], v[182:185], v[58:61]
	v_mfma_f32_16x16x32_bf16 v[58:61], v[156:159], v[186:189], v[58:61]
	v_mfma_f32_16x16x32_bf16 v[46:49], v[152:155], v[190:193], v[46:49]
	v_mfma_f32_16x16x32_bf16 v[46:49], v[156:159], v[194:197], v[46:49]
	v_mfma_f32_16x16x32_bf16 v[30:33], v[152:155], v[198:201], v[30:33]
	v_mfma_f32_16x16x32_bf16 v[30:33], v[156:159], v[202:205], v[30:33]
	v_mfma_f32_16x16x32_bf16 v[14:17], v[152:155], v[206:209], v[14:17]
	v_mfma_f32_16x16x32_bf16 v[14:17], v[156:159], v[210:213], v[14:17]
	s_setprio 0
	s_setprio 1
	v_mfma_f32_16x16x32_bf16 v[50:53], v[160:163], v[182:185], v[50:53]
	v_mfma_f32_16x16x32_bf16 v[50:53], v[170:173], v[186:189], v[50:53]
	v_mfma_f32_16x16x32_bf16 v[34:37], v[160:163], v[190:193], v[34:37]
	v_mfma_f32_16x16x32_bf16 v[34:37], v[170:173], v[194:197], v[34:37]
	v_mfma_f32_16x16x32_bf16 v[18:21], v[160:163], v[198:201], v[18:21]
	v_mfma_f32_16x16x32_bf16 v[18:21], v[170:173], v[202:205], v[18:21]
	v_mfma_f32_16x16x32_bf16 v[6:9], v[160:163], v[206:209], v[6:9]
	v_mfma_f32_16x16x32_bf16 v[6:9], v[170:173], v[210:213], v[6:9]
	v_mfma_f32_16x16x32_bf16 v[42:45], v[174:177], v[182:185], v[42:45]
	v_mfma_f32_16x16x32_bf16 v[42:45], v[178:181], v[186:189], v[42:45]
	v_mfma_f32_16x16x32_bf16 v[26:29], v[174:177], v[190:193], v[26:29]
	v_mfma_f32_16x16x32_bf16 v[26:29], v[178:181], v[194:197], v[26:29]
	v_mfma_f32_16x16x32_bf16 v[10:13], v[174:177], v[198:201], v[10:13]
	v_mfma_f32_16x16x32_bf16 v[10:13], v[178:181], v[202:205], v[10:13]
	v_mfma_f32_16x16x32_bf16 v[2:5], v[174:177], v[206:209], v[2:5]
	v_mfma_f32_16x16x32_bf16 v[2:5], v[178:181], v[210:213], v[2:5]
	s_setprio 0
	s_barrier
	s_add_i32 s22, s22, 2
	s_add_u32 s48, s48, 0x100
	s_addc_u32 s49, s49, 0
	s_add_u32 s20, s20, 0x100
	s_addc_u32 s21, s21, 0
	s_cmp_gt_u32 s22, 29
	s_cbranch_scc0 .LBB0_132
	s_and_b64 vcc, exec, s[10:11]
	s_cbranch_vccz .LBB0_135
	s_barrier

.LBB0_238:
	s_add_u32 s10, s12, 0x100
	s_addc_u32 s11, s13, 0
	s_add_i32 s23, 0, 0x10000
	s_cmpk_eq_i32 s22, 0x52
	s_cselect_b32 vcc_hi, s47, s11
	s_cselect_b32 vcc_lo, s46, s10
	s_cselect_b32 s51, s49, s21
	s_cselect_b32 s50, s48, s20
	s_add_i32 s24, 0, 0x14000
	v_add_u32_e32 v142, s23, v194
	v_add_u32_e32 v158, s24, v194
	ds_read_b128 v[122:125], v142
	ds_read_b128 v[126:129], v142 offset:1024
	ds_read_b128 v[138:141], v142 offset:2048
	ds_read_b128 v[142:145], v142 offset:3072
	ds_read_b128 v[146:149], v158
	ds_read_b128 v[150:153], v158 offset:1024
	ds_read_b128 v[154:157], v158 offset:2048
	ds_read_b128 v[158:161], v158 offset:3072
	v_lshl_add_u64 v[212:213], s[12:13], 0, v[170:171]
	s_add_i32 m0, s57, 0xc000
	ds_read_b128 v[174:177], v198
	ds_read_b128 v[178:181], v198 offset:1024
	ds_read_b128 v[182:185], v198 offset:2048
	ds_read_b128 v[186:189], v198 offset:3072
	ds_read_b128 v[190:193], v198 offset:4096
	ds_read_b128 v[200:203], v198 offset:5120
	ds_read_b128 v[204:207], v198 offset:6144
	ds_read_b128 v[208:211], v198 offset:7168
	global_load_lds_dwordx4 v[212:213], off
	v_lshl_add_u64 v[212:213], s[12:13], 0, v[172:173]
	s_add_i32 m0, s57, 0xe000
	s_nop 0
	global_load_lds_dwordx4 v[212:213], off
	s_waitcnt vmcnt(8)
	s_waitcnt lgkmcnt(0)
	s_barrier
	s_setprio 1
	s_waitcnt lgkmcnt(0)
	v_mfma_f32_16x16x32_bf16 v[134:137], v[122:125], v[174:177], v[134:137]
	v_mfma_f32_16x16x32_bf16 v[134:137], v[126:129], v[178:181], v[134:137]
	v_mfma_f32_16x16x32_bf16 v[110:113], v[122:125], v[182:185], v[110:113]
	v_mfma_f32_16x16x32_bf16 v[110:113], v[126:129], v[186:189], v[110:113]
	v_mfma_f32_16x16x32_bf16 v[94:97], v[122:125], v[190:193], v[94:97]
	v_mfma_f32_16x16x32_bf16 v[94:97], v[126:129], v[200:203], v[94:97]
	v_mfma_f32_16x16x32_bf16 v[78:81], v[122:125], v[204:207], v[78:81]
	v_mfma_f32_16x16x32_bf16 v[78:81], v[126:129], v[208:211], v[78:81]
	v_mfma_f32_16x16x32_bf16 v[130:133], v[138:141], v[174:177], v[130:133]
	v_mfma_f32_16x16x32_bf16 v[130:133], v[142:145], v[178:181], v[130:133]
	v_mfma_f32_16x16x32_bf16 v[106:109], v[138:141], v[182:185], v[106:109]
	v_mfma_f32_16x16x32_bf16 v[106:109], v[142:145], v[186:189], v[106:109]
	v_mfma_f32_16x16x32_bf16 v[90:93], v[138:141], v[190:193], v[90:93]
	v_mfma_f32_16x16x32_bf16 v[90:93], v[142:145], v[200:203], v[90:93]
	v_mfma_f32_16x16x32_bf16 v[74:77], v[138:141], v[204:207], v[74:77]
	v_mfma_f32_16x16x32_bf16 v[74:77], v[142:145], v[208:211], v[74:77]
	s_setprio 0
	s_setprio 1
	v_mfma_f32_16x16x32_bf16 v[118:121], v[146:149], v[174:177], v[118:121]
	v_mfma_f32_16x16x32_bf16 v[118:121], v[150:153], v[178:181], v[118:121]
	v_mfma_f32_16x16x32_bf16 v[102:105], v[146:149], v[182:185], v[102:105]
	v_mfma_f32_16x16x32_bf16 v[102:105], v[150:153], v[186:189], v[102:105]
	v_mfma_f32_16x16x32_bf16 v[86:89], v[146:149], v[190:193], v[86:89]
	v_mfma_f32_16x16x32_bf16 v[86:89], v[150:153], v[200:203], v[86:89]
	v_mfma_f32_16x16x32_bf16 v[70:73], v[146:149], v[204:207], v[70:73]
	v_mfma_f32_16x16x32_bf16 v[70:73], v[150:153], v[208:211], v[70:73]
	v_mfma_f32_16x16x32_bf16 v[114:117], v[154:157], v[174:177], v[114:117]
	v_mfma_f32_16x16x32_bf16 v[114:117], v[158:161], v[178:181], v[114:117]
	v_mfma_f32_16x16x32_bf16 v[98:101], v[154:157], v[182:185], v[98:101]
	v_mfma_f32_16x16x32_bf16 v[98:101], v[158:161], v[186:189], v[98:101]
	v_mfma_f32_16x16x32_bf16 v[82:85], v[154:157], v[190:193], v[82:85]
	v_mfma_f32_16x16x32_bf16 v[82:85], v[158:161], v[200:203], v[82:85]
	v_mfma_f32_16x16x32_bf16 v[66:69], v[154:157], v[204:207], v[66:69]
	v_mfma_f32_16x16x32_bf16 v[66:69], v[158:161], v[208:211], v[66:69]
	s_setprio 0
	s_barrier
	s_add_i32 s12, s23, s42
	v_lshl_add_u64 v[212:213], s[50:51], 0, v[164:165]
	s_mov_b32 m0, s12
	ds_read_b128 v[174:177], v198 offset:16384
	ds_read_b128 v[178:181], v198 offset:17408
	ds_read_b128 v[182:185], v198 offset:18432
	ds_read_b128 v[186:189], v198 offset:19456
	ds_read_b128 v[190:193], v198 offset:20480
	ds_read_b128 v[200:203], v198 offset:21504
	ds_read_b128 v[204:207], v198 offset:22528
	ds_read_b128 v[208:211], v198 offset:23552
	global_load_lds_dwordx4 v[212:213], off
	s_add_i32 m0, s12, 0x2000
	s_add_u32 s12, s50, 0x158000
	v_lshl_add_u64 v[232:233], s[50:51], 0, v[168:169]
	s_addc_u32 s13, s51, 0
	s_add_i32 s23, s24, s42
	global_load_lds_dwordx4 v[232:233], off
	v_lshl_add_u64 v[234:235], s[12:13], 0, v[164:165]
	s_mov_b32 m0, s23
	v_lshl_add_u64 v[236:237], vcc, 0, v[166:167]
	global_load_lds_dwordx4 v[234:235], off
	v_lshl_add_u64 v[234:235], s[12:13], 0, v[168:169]
	s_add_i32 m0, s23, 0x2000
	s_nop 0
	global_load_lds_dwordx4 v[234:235], off
	v_lshl_add_u64 v[234:235], vcc, 0, v[162:163]
	s_mov_b32 m0, s57
	s_nop 0
	global_load_lds_dwordx4 v[234:235], off
	s_mov_b32 m0, s58
	s_nop 0
	global_load_lds_dwordx4 v[236:237], off
	s_waitcnt vmcnt(8)
	s_waitcnt lgkmcnt(0)
	s_barrier
	s_setprio 1
	s_waitcnt lgkmcnt(0)
	v_mfma_f32_16x16x32_bf16 v[62:65], v[122:125], v[174:177], v[62:65]
	v_mfma_f32_16x16x32_bf16 v[62:65], v[126:129], v[178:181], v[62:65]
	v_mfma_f32_16x16x32_bf16 v[46:49], v[122:125], v[182:185], v[46:49]
	v_mfma_f32_16x16x32_bf16 v[46:49], v[126:129], v[186:189], v[46:49]
	v_mfma_f32_16x16x32_bf16 v[30:33], v[122:125], v[190:193], v[30:33]
	v_mfma_f32_16x16x32_bf16 v[30:33], v[126:129], v[200:203], v[30:33]
	v_mfma_f32_16x16x32_bf16 v[14:17], v[122:125], v[204:207], v[14:17]
	v_mfma_f32_16x16x32_bf16 v[14:17], v[126:129], v[208:211], v[14:17]
	v_mfma_f32_16x16x32_bf16 v[58:61], v[138:141], v[174:177], v[58:61]
	v_mfma_f32_16x16x32_bf16 v[58:61], v[142:145], v[178:181], v[58:61]
	v_mfma_f32_16x16x32_bf16 v[42:45], v[138:141], v[182:185], v[42:45]
	v_mfma_f32_16x16x32_bf16 v[42:45], v[142:145], v[186:189], v[42:45]
	v_mfma_f32_16x16x32_bf16 v[26:29], v[138:141], v[190:193], v[26:29]
	v_mfma_f32_16x16x32_bf16 v[26:29], v[142:145], v[200:203], v[26:29]
	v_mfma_f32_16x16x32_bf16 v[10:13], v[138:141], v[204:207], v[10:13]
	v_mfma_f32_16x16x32_bf16 v[10:13], v[142:145], v[208:211], v[10:13]
	s_setprio 0
	s_setprio 1
	v_mfma_f32_16x16x32_bf16 v[54:57], v[146:149], v[174:177], v[54:57]
	v_mfma_f32_16x16x32_bf16 v[54:57], v[150:153], v[178:181], v[54:57]
	v_mfma_f32_16x16x32_bf16 v[38:41], v[146:149], v[182:185], v[38:41]
	v_mfma_f32_16x16x32_bf16 v[38:41], v[150:153], v[186:189], v[38:41]
	v_mfma_f32_16x16x32_bf16 v[22:25], v[146:149], v[190:193], v[22:25]
	v_mfma_f32_16x16x32_bf16 v[22:25], v[150:153], v[200:203], v[22:25]
	v_mfma_f32_16x16x32_bf16 v[6:9], v[146:149], v[204:207], v[6:9]
	v_mfma_f32_16x16x32_bf16 v[6:9], v[150:153], v[208:211], v[6:9]
	v_mfma_f32_16x16x32_bf16 v[50:53], v[154:157], v[174:177], v[50:53]
	v_mfma_f32_16x16x32_bf16 v[50:53], v[158:161], v[178:181], v[50:53]
	v_mfma_f32_16x16x32_bf16 v[34:37], v[154:157], v[182:185], v[34:37]
	v_mfma_f32_16x16x32_bf16 v[34:37], v[158:161], v[186:189], v[34:37]
	v_mfma_f32_16x16x32_bf16 v[18:21], v[154:157], v[190:193], v[18:21]
	v_mfma_f32_16x16x32_bf16 v[18:21], v[158:161], v[200:203], v[18:21]
	v_mfma_f32_16x16x32_bf16 v[2:5], v[154:157], v[204:207], v[2:5]
	v_mfma_f32_16x16x32_bf16 v[2:5], v[158:161], v[208:211], v[2:5]
	s_setprio 0
	s_barrier
	s_add_i32 s23, 0, 0x18000
	s_add_i32 s24, 0, 0x1c000
	v_add_u32_e32 v142, s23, v194
	v_add_u32_e32 v158, s24, v194
	ds_read_b128 v[122:125], v142
	ds_read_b128 v[126:129], v142 offset:1024
	ds_read_b128 v[138:141], v142 offset:2048
	ds_read_b128 v[142:145], v142 offset:3072
	ds_read_b128 v[146:149], v158
	ds_read_b128 v[150:153], v158 offset:1024
	ds_read_b128 v[154:157], v158 offset:2048
	ds_read_b128 v[158:161], v158 offset:3072
	s_add_u32 s12, vcc_lo, 0x158000
	s_addc_u32 s13, vcc_hi, 0
	s_mov_b32 m0, s67
	v_lshl_add_u64 v[238:239], s[12:13], 0, v[162:163]
	ds_read_b128 v[174:177], v198 offset:32768
	ds_read_b128 v[178:181], v198 offset:33792
	ds_read_b128 v[182:185], v198 offset:34816
	ds_read_b128 v[186:189], v198 offset:35840
	ds_read_b128 v[190:193], v198 offset:36864
	ds_read_b128 v[200:203], v198 offset:37888
	ds_read_b128 v[204:207], v198 offset:38912
	ds_read_b128 v[208:211], v198 offset:39936
	global_load_lds_dwordx4 v[238:239], off
	v_lshl_add_u64 v[238:239], s[12:13], 0, v[166:167]
	s_mov_b32 m0, s76
	s_nop 0
	global_load_lds_dwordx4 v[238:239], off
	s_waitcnt vmcnt(8)
	s_waitcnt lgkmcnt(0)
	s_barrier
	s_setprio 1
	s_waitcnt lgkmcnt(0)
	v_mfma_f32_16x16x32_bf16 v[134:137], v[122:125], v[174:177], v[134:137]
	v_mfma_f32_16x16x32_bf16 v[134:137], v[126:129], v[178:181], v[134:137]
	v_mfma_f32_16x16x32_bf16 v[110:113], v[122:125], v[182:185], v[110:113]
	v_mfma_f32_16x16x32_bf16 v[110:113], v[126:129], v[186:189], v[110:113]
	v_mfma_f32_16x16x32_bf16 v[94:97], v[122:125], v[190:193], v[94:97]
	v_mfma_f32_16x16x32_bf16 v[94:97], v[126:129], v[200:203], v[94:97]
	v_mfma_f32_16x16x32_bf16 v[78:81], v[122:125], v[204:207], v[78:81]
	v_mfma_f32_16x16x32_bf16 v[78:81], v[126:129], v[208:211], v[78:81]
	v_mfma_f32_16x16x32_bf16 v[130:133], v[138:141], v[174:177], v[130:133]
	v_mfma_f32_16x16x32_bf16 v[130:133], v[142:145], v[178:181], v[130:133]
	v_mfma_f32_16x16x32_bf16 v[106:109], v[138:141], v[182:185], v[106:109]
	v_mfma_f32_16x16x32_bf16 v[106:109], v[142:145], v[186:189], v[106:109]
	v_mfma_f32_16x16x32_bf16 v[90:93], v[138:141], v[190:193], v[90:93]
	v_mfma_f32_16x16x32_bf16 v[90:93], v[142:145], v[200:203], v[90:93]
	v_mfma_f32_16x16x32_bf16 v[74:77], v[138:141], v[204:207], v[74:77]
	v_mfma_f32_16x16x32_bf16 v[74:77], v[142:145], v[208:211], v[74:77]
	s_setprio 0
	s_setprio 1
	v_mfma_f32_16x16x32_bf16 v[118:121], v[146:149], v[174:177], v[118:121]
	v_mfma_f32_16x16x32_bf16 v[118:121], v[150:153], v[178:181], v[118:121]
	v_mfma_f32_16x16x32_bf16 v[102:105], v[146:149], v[182:185], v[102:105]
	v_mfma_f32_16x16x32_bf16 v[102:105], v[150:153], v[186:189], v[102:105]
	v_mfma_f32_16x16x32_bf16 v[86:89], v[146:149], v[190:193], v[86:89]
	v_mfma_f32_16x16x32_bf16 v[86:89], v[150:153], v[200:203], v[86:89]
	v_mfma_f32_16x16x32_bf16 v[70:73], v[146:149], v[204:207], v[70:73]
	v_mfma_f32_16x16x32_bf16 v[70:73], v[150:153], v[208:211], v[70:73]
	v_mfma_f32_16x16x32_bf16 v[114:117], v[154:157], v[174:177], v[114:117]
	v_mfma_f32_16x16x32_bf16 v[114:117], v[158:161], v[178:181], v[114:117]
	v_mfma_f32_16x16x32_bf16 v[98:101], v[154:157], v[182:185], v[98:101]
	v_mfma_f32_16x16x32_bf16 v[98:101], v[158:161], v[186:189], v[98:101]
	v_mfma_f32_16x16x32_bf16 v[82:85], v[154:157], v[190:193], v[82:85]
	v_mfma_f32_16x16x32_bf16 v[82:85], v[158:161], v[200:203], v[82:85]
	v_mfma_f32_16x16x32_bf16 v[66:69], v[154:157], v[204:207], v[66:69]
	v_mfma_f32_16x16x32_bf16 v[66:69], v[158:161], v[208:211], v[66:69]
	s_setprio 0
	s_barrier
	s_add_i32 s12, s23, s42
	v_lshl_add_u64 v[212:213], v[212:213], 0, s[62:63]
	s_mov_b32 m0, s12
	ds_read_b128 v[174:177], v198 offset:49152
	ds_read_b128 v[178:181], v198 offset:50176
	ds_read_b128 v[182:185], v198 offset:51200
	ds_read_b128 v[186:189], v198 offset:52224
	ds_read_b128 v[190:193], v198 offset:53248
	ds_read_b128 v[200:203], v198 offset:54272
	ds_read_b128 v[204:207], v198 offset:55296
	ds_read_b128 v[208:211], v198 offset:56320
	global_load_lds_dwordx4 v[212:213], off
	s_add_i32 m0, s12, 0x2000
	s_add_u32 s12, s50, 0x158080
	v_lshl_add_u64 v[212:213], v[232:233], 0, s[62:63]
	s_addc_u32 s13, s51, 0
	s_add_i32 s23, s24, s42
	global_load_lds_dwordx4 v[212:213], off
	v_lshl_add_u64 v[212:213], s[12:13], 0, v[164:165]
	s_mov_b32 m0, s23
	s_nop 0
	global_load_lds_dwordx4 v[212:213], off
	v_lshl_add_u64 v[212:213], s[12:13], 0, v[168:169]
	s_add_i32 m0, s23, 0x2000
	s_nop 0
	global_load_lds_dwordx4 v[212:213], off
	v_lshl_add_u64 v[212:213], v[234:235], 0, s[62:63]
	s_mov_b32 m0, s1
	s_nop 0
	global_load_lds_dwordx4 v[212:213], off
	v_lshl_add_u64 v[212:213], v[236:237], 0, s[62:63]
	s_mov_b32 m0, s52
	s_nop 0
	global_load_lds_dwordx4 v[212:213], off
	s_waitcnt vmcnt(8)
	s_waitcnt lgkmcnt(0)
	s_barrier
	s_setprio 1
	s_waitcnt lgkmcnt(0)
	v_mfma_f32_16x16x32_bf16 v[62:65], v[122:125], v[174:177], v[62:65]
	v_mfma_f32_16x16x32_bf16 v[62:65], v[126:129], v[178:181], v[62:65]
	v_mfma_f32_16x16x32_bf16 v[46:49], v[122:125], v[182:185], v[46:49]
	v_mfma_f32_16x16x32_bf16 v[46:49], v[126:129], v[186:189], v[46:49]
	v_mfma_f32_16x16x32_bf16 v[30:33], v[122:125], v[190:193], v[30:33]
	v_mfma_f32_16x16x32_bf16 v[30:33], v[126:129], v[200:203], v[30:33]
	v_mfma_f32_16x16x32_bf16 v[14:17], v[122:125], v[204:207], v[14:17]
	v_mfma_f32_16x16x32_bf16 v[14:17], v[126:129], v[208:211], v[14:17]
	v_mfma_f32_16x16x32_bf16 v[58:61], v[138:141], v[174:177], v[58:61]
	v_mfma_f32_16x16x32_bf16 v[58:61], v[142:145], v[178:181], v[58:61]
	v_mfma_f32_16x16x32_bf16 v[42:45], v[138:141], v[182:185], v[42:45]
	v_mfma_f32_16x16x32_bf16 v[42:45], v[142:145], v[186:189], v[42:45]
	v_mfma_f32_16x16x32_bf16 v[26:29], v[138:141], v[190:193], v[26:29]
	v_mfma_f32_16x16x32_bf16 v[26:29], v[142:145], v[200:203], v[26:29]
	v_mfma_f32_16x16x32_bf16 v[10:13], v[138:141], v[204:207], v[10:13]
	v_mfma_f32_16x16x32_bf16 v[10:13], v[142:145], v[208:211], v[10:13]
	s_setprio 0
	s_setprio 1
	v_mfma_f32_16x16x32_bf16 v[54:57], v[146:149], v[174:177], v[54:57]
	v_mfma_f32_16x16x32_bf16 v[54:57], v[150:153], v[178:181], v[54:57]
	v_mfma_f32_16x16x32_bf16 v[38:41], v[146:149], v[182:185], v[38:41]
	v_mfma_f32_16x16x32_bf16 v[38:41], v[150:153], v[186:189], v[38:41]
	v_mfma_f32_16x16x32_bf16 v[22:25], v[146:149], v[190:193], v[22:25]
	v_mfma_f32_16x16x32_bf16 v[22:25], v[150:153], v[200:203], v[22:25]
	v_mfma_f32_16x16x32_bf16 v[6:9], v[146:149], v[204:207], v[6:9]
	v_mfma_f32_16x16x32_bf16 v[6:9], v[150:153], v[208:211], v[6:9]
	v_mfma_f32_16x16x32_bf16 v[50:53], v[154:157], v[174:177], v[50:53]
	v_mfma_f32_16x16x32_bf16 v[50:53], v[158:161], v[178:181], v[50:53]
	v_mfma_f32_16x16x32_bf16 v[34:37], v[154:157], v[182:185], v[34:37]
	v_mfma_f32_16x16x32_bf16 v[34:37], v[158:161], v[186:189], v[34:37]
	v_mfma_f32_16x16x32_bf16 v[18:21], v[154:157], v[190:193], v[18:21]
	v_mfma_f32_16x16x32_bf16 v[18:21], v[158:161], v[200:203], v[18:21]
	v_mfma_f32_16x16x32_bf16 v[2:5], v[154:157], v[204:207], v[2:5]
	v_mfma_f32_16x16x32_bf16 v[2:5], v[158:161], v[208:211], v[2:5]
	s_setprio 0
	s_barrier
	s_add_i32 s22, s22, 2
	s_add_u32 s20, s20, 0x100
	s_addc_u32 s21, s21, 0
	s_cmpk_gt_u32 s22, 0x53
	s_mov_b64 s[12:13], s[10:11]
	s_cbranch_scc0 .LBB0_238
	s_and_b64 vcc, exec, s[2:3]
	s_cbranch_vccz .LBB0_241
	s_barrier

.LBB0_340:
	s_add_u32 s22, s46, 0xfff80080
	s_addc_u32 s23, s47, -1
	s_add_i32 s24, 0, 0x10000
	s_cmp_eq_u32 s21, 28
	s_cselect_b32 s51, s1, s23
	s_cselect_b32 s50, s13, s22
	v_add_u32_e32 v148, s24, v152
	s_cselect_b32 s49, s11, s20
	s_cselect_b32 s48, s18, s19
	s_add_i32 s25, 0, 0x14000
	ds_read_b128 v[144:147], v148
	ds_read_b128 v[156:159], v148 offset:1024
	ds_read_b128 v[160:163], v148 offset:2048
	ds_read_b128 v[164:167], v148 offset:3072
	v_add_u32_e32 v148, s25, v152
	ds_read_b128 v[168:171], v148
	ds_read_b128 v[172:175], v148 offset:1024
	ds_read_b128 v[176:179], v148 offset:2048
	ds_read_b128 v[180:183], v148 offset:3072
	v_lshl_add_u64 v[148:149], s[46:47], 0, v[140:141]
	s_add_i32 m0, s3, 0xc000
	ds_read_b128 v[184:187], v154
	ds_read_b128 v[188:191], v154 offset:1024
	ds_read_b128 v[192:195], v154 offset:2048
	ds_read_b128 v[196:199], v154 offset:3072
	ds_read_b128 v[200:203], v154 offset:4096
	ds_read_b128 v[204:207], v154 offset:5120
	ds_read_b128 v[208:211], v154 offset:6144
	ds_read_b128 v[232:235], v154 offset:7168
	global_load_lds_dwordx4 v[148:149], off
	v_lshl_add_u64 v[148:149], s[46:47], 0, v[142:143]
	s_add_i32 m0, s3, 0xe000
	s_nop 0
	global_load_lds_dwordx4 v[148:149], off
	s_waitcnt vmcnt(8)
	s_waitcnt lgkmcnt(0)
	s_barrier
	s_setprio 1
	s_waitcnt lgkmcnt(0)
	v_mfma_f32_16x16x32_bf16 v[126:129], v[144:147], v[184:187], v[126:129]
	v_mfma_f32_16x16x32_bf16 v[126:129], v[156:159], v[188:191], v[126:129]
	v_mfma_f32_16x16x32_bf16 v[110:113], v[144:147], v[192:195], v[110:113]
	v_mfma_f32_16x16x32_bf16 v[110:113], v[156:159], v[196:199], v[110:113]
	v_mfma_f32_16x16x32_bf16 v[94:97], v[144:147], v[200:203], v[94:97]
	v_mfma_f32_16x16x32_bf16 v[94:97], v[156:159], v[204:207], v[94:97]
	v_mfma_f32_16x16x32_bf16 v[78:81], v[144:147], v[208:211], v[78:81]
	v_mfma_f32_16x16x32_bf16 v[78:81], v[156:159], v[232:235], v[78:81]
	v_mfma_f32_16x16x32_bf16 v[122:125], v[160:163], v[184:187], v[122:125]
	v_mfma_f32_16x16x32_bf16 v[122:125], v[164:167], v[188:191], v[122:125]
	v_mfma_f32_16x16x32_bf16 v[106:109], v[160:163], v[192:195], v[106:109]
	v_mfma_f32_16x16x32_bf16 v[106:109], v[164:167], v[196:199], v[106:109]
	v_mfma_f32_16x16x32_bf16 v[90:93], v[160:163], v[200:203], v[90:93]
	v_mfma_f32_16x16x32_bf16 v[90:93], v[164:167], v[204:207], v[90:93]
	v_mfma_f32_16x16x32_bf16 v[74:77], v[160:163], v[208:211], v[74:77]
	v_mfma_f32_16x16x32_bf16 v[74:77], v[164:167], v[232:235], v[74:77]
	s_setprio 0
	s_setprio 1
	v_mfma_f32_16x16x32_bf16 v[118:121], v[168:171], v[184:187], v[118:121]
	v_mfma_f32_16x16x32_bf16 v[118:121], v[172:175], v[188:191], v[118:121]
	v_mfma_f32_16x16x32_bf16 v[102:105], v[168:171], v[192:195], v[102:105]
	v_mfma_f32_16x16x32_bf16 v[102:105], v[172:175], v[196:199], v[102:105]
	v_mfma_f32_16x16x32_bf16 v[86:89], v[168:171], v[200:203], v[86:89]
	v_mfma_f32_16x16x32_bf16 v[86:89], v[172:175], v[204:207], v[86:89]
	v_mfma_f32_16x16x32_bf16 v[70:73], v[168:171], v[208:211], v[70:73]
	v_mfma_f32_16x16x32_bf16 v[70:73], v[172:175], v[232:235], v[70:73]
	v_mfma_f32_16x16x32_bf16 v[114:117], v[176:179], v[184:187], v[114:117]
	v_mfma_f32_16x16x32_bf16 v[114:117], v[180:183], v[188:191], v[114:117]
	v_mfma_f32_16x16x32_bf16 v[98:101], v[176:179], v[192:195], v[98:101]
	v_mfma_f32_16x16x32_bf16 v[98:101], v[180:183], v[196:199], v[98:101]
	v_mfma_f32_16x16x32_bf16 v[82:85], v[176:179], v[200:203], v[82:85]
	v_mfma_f32_16x16x32_bf16 v[82:85], v[180:183], v[204:207], v[82:85]
	v_mfma_f32_16x16x32_bf16 v[66:69], v[176:179], v[208:211], v[66:69]
	v_mfma_f32_16x16x32_bf16 v[66:69], v[180:183], v[232:235], v[66:69]
	s_setprio 0
	s_barrier
	s_add_i32 s22, s24, s16
	v_lshl_add_u64 v[148:149], s[48:49], 0, v[134:135]
	s_mov_b32 m0, s22
	ds_read_b128 v[184:187], v154 offset:16384
	ds_read_b128 v[188:191], v154 offset:17408
	ds_read_b128 v[192:195], v154 offset:18432
	ds_read_b128 v[196:199], v154 offset:19456
	ds_read_b128 v[200:203], v154 offset:20480
	ds_read_b128 v[204:207], v154 offset:21504
	ds_read_b128 v[208:211], v154 offset:22528
	ds_read_b128 v[232:235], v154 offset:23552
	global_load_lds_dwordx4 v[148:149], off
	s_add_i32 m0, s22, 0x2000
	s_add_u32 s22, s48, 0x80000
	v_lshl_add_u64 v[212:213], s[48:49], 0, v[130:131]
	s_addc_u32 s23, s49, 0
	s_add_i32 s24, s25, s16
	global_load_lds_dwordx4 v[212:213], off
	v_lshl_add_u64 v[236:237], s[22:23], 0, v[134:135]
	s_mov_b32 m0, s24
	v_lshl_add_u64 v[238:239], s[50:51], 0, v[132:133]
	global_load_lds_dwordx4 v[236:237], off
	v_lshl_add_u64 v[236:237], s[22:23], 0, v[130:131]
	s_add_i32 m0, s24, 0x2000
	s_nop 0
	global_load_lds_dwordx4 v[236:237], off
	v_lshl_add_u64 v[236:237], s[50:51], 0, v[136:137]
	s_mov_b32 m0, s3
	s_nop 0
	global_load_lds_dwordx4 v[236:237], off
	s_mov_b32 m0, s55
	s_nop 0
	global_load_lds_dwordx4 v[238:239], off
	s_waitcnt vmcnt(8)
	s_waitcnt lgkmcnt(0)
	s_barrier
	s_setprio 1
	s_waitcnt lgkmcnt(0)
	v_mfma_f32_16x16x32_bf16 v[62:65], v[144:147], v[184:187], v[62:65]
	v_mfma_f32_16x16x32_bf16 v[62:65], v[156:159], v[188:191], v[62:65]
	v_mfma_f32_16x16x32_bf16 v[46:49], v[144:147], v[192:195], v[46:49]
	v_mfma_f32_16x16x32_bf16 v[46:49], v[156:159], v[196:199], v[46:49]
	v_mfma_f32_16x16x32_bf16 v[30:33], v[144:147], v[200:203], v[30:33]
	v_mfma_f32_16x16x32_bf16 v[30:33], v[156:159], v[204:207], v[30:33]
	v_mfma_f32_16x16x32_bf16 v[14:17], v[144:147], v[208:211], v[14:17]
	v_mfma_f32_16x16x32_bf16 v[14:17], v[156:159], v[232:235], v[14:17]
	v_mfma_f32_16x16x32_bf16 v[58:61], v[160:163], v[184:187], v[58:61]
	v_mfma_f32_16x16x32_bf16 v[58:61], v[164:167], v[188:191], v[58:61]
	v_mfma_f32_16x16x32_bf16 v[42:45], v[160:163], v[192:195], v[42:45]
	v_mfma_f32_16x16x32_bf16 v[42:45], v[164:167], v[196:199], v[42:45]
	v_mfma_f32_16x16x32_bf16 v[26:29], v[160:163], v[200:203], v[26:29]
	v_mfma_f32_16x16x32_bf16 v[26:29], v[164:167], v[204:207], v[26:29]
	v_mfma_f32_16x16x32_bf16 v[10:13], v[160:163], v[208:211], v[10:13]
	v_mfma_f32_16x16x32_bf16 v[10:13], v[164:167], v[232:235], v[10:13]
	s_setprio 0
	s_setprio 1
	v_mfma_f32_16x16x32_bf16 v[54:57], v[168:171], v[184:187], v[54:57]
	v_mfma_f32_16x16x32_bf16 v[54:57], v[172:175], v[188:191], v[54:57]
	v_mfma_f32_16x16x32_bf16 v[38:41], v[168:171], v[192:195], v[38:41]
	v_mfma_f32_16x16x32_bf16 v[38:41], v[172:175], v[196:199], v[38:41]
	v_mfma_f32_16x16x32_bf16 v[22:25], v[168:171], v[200:203], v[22:25]
	v_mfma_f32_16x16x32_bf16 v[22:25], v[172:175], v[204:207], v[22:25]
	v_mfma_f32_16x16x32_bf16 v[6:9], v[168:171], v[208:211], v[6:9]
	v_mfma_f32_16x16x32_bf16 v[6:9], v[172:175], v[232:235], v[6:9]
	v_mfma_f32_16x16x32_bf16 v[50:53], v[176:179], v[184:187], v[50:53]
	v_mfma_f32_16x16x32_bf16 v[50:53], v[180:183], v[188:191], v[50:53]
	v_mfma_f32_16x16x32_bf16 v[34:37], v[176:179], v[192:195], v[34:37]
	v_mfma_f32_16x16x32_bf16 v[34:37], v[180:183], v[196:199], v[34:37]
	v_mfma_f32_16x16x32_bf16 v[18:21], v[176:179], v[200:203], v[18:21]
	v_mfma_f32_16x16x32_bf16 v[18:21], v[180:183], v[204:207], v[18:21]
	v_mfma_f32_16x16x32_bf16 v[2:5], v[176:179], v[208:211], v[2:5]
	v_mfma_f32_16x16x32_bf16 v[2:5], v[180:183], v[232:235], v[2:5]
	s_setprio 0
	s_barrier
	s_add_i32 s24, 0, 0x18000
	v_add_u32_e32 v155, s24, v152
	s_add_i32 s25, 0, 0x1c000
	ds_read_b128 v[144:147], v155
	ds_read_b128 v[156:159], v155 offset:1024
	ds_read_b128 v[160:163], v155 offset:2048
	ds_read_b128 v[164:167], v155 offset:3072
	v_add_u32_e32 v155, s25, v152
	ds_read_b128 v[168:171], v155
	ds_read_b128 v[172:175], v155 offset:1024
	ds_read_b128 v[176:179], v155 offset:2048
	ds_read_b128 v[180:183], v155 offset:3072
	s_add_u32 s22, s50, 0x80000
	s_addc_u32 s23, s51, 0
	s_mov_b32 m0, s57
	v_lshl_add_u64 v[240:241], s[22:23], 0, v[136:137]
	ds_read_b128 v[184:187], v154 offset:32768
	ds_read_b128 v[188:191], v154 offset:33792
	ds_read_b128 v[192:195], v154 offset:34816
	ds_read_b128 v[196:199], v154 offset:35840
	ds_read_b128 v[200:203], v154 offset:36864
	ds_read_b128 v[204:207], v154 offset:37888
	ds_read_b128 v[208:211], v154 offset:38912
	ds_read_b128 v[232:235], v154 offset:39936
	global_load_lds_dwordx4 v[240:241], off
	v_lshl_add_u64 v[240:241], s[22:23], 0, v[132:133]
	s_mov_b32 m0, s68
	s_nop 0
	global_load_lds_dwordx4 v[240:241], off
	s_waitcnt vmcnt(8)
	s_waitcnt lgkmcnt(0)
	s_barrier
	s_setprio 1
	s_waitcnt lgkmcnt(0)
	v_mfma_f32_16x16x32_bf16 v[126:129], v[144:147], v[184:187], v[126:129]
	v_mfma_f32_16x16x32_bf16 v[126:129], v[156:159], v[188:191], v[126:129]
	v_mfma_f32_16x16x32_bf16 v[110:113], v[144:147], v[192:195], v[110:113]
	v_mfma_f32_16x16x32_bf16 v[110:113], v[156:159], v[196:199], v[110:113]
	v_mfma_f32_16x16x32_bf16 v[94:97], v[144:147], v[200:203], v[94:97]
	v_mfma_f32_16x16x32_bf16 v[94:97], v[156:159], v[204:207], v[94:97]
	v_mfma_f32_16x16x32_bf16 v[78:81], v[144:147], v[208:211], v[78:81]
	v_mfma_f32_16x16x32_bf16 v[78:81], v[156:159], v[232:235], v[78:81]
	v_mfma_f32_16x16x32_bf16 v[122:125], v[160:163], v[184:187], v[122:125]
	v_mfma_f32_16x16x32_bf16 v[122:125], v[164:167], v[188:191], v[122:125]
	v_mfma_f32_16x16x32_bf16 v[106:109], v[160:163], v[192:195], v[106:109]
	v_mfma_f32_16x16x32_bf16 v[106:109], v[164:167], v[196:199], v[106:109]
	v_mfma_f32_16x16x32_bf16 v[90:93], v[160:163], v[200:203], v[90:93]
	v_mfma_f32_16x16x32_bf16 v[90:93], v[164:167], v[204:207], v[90:93]
	v_mfma_f32_16x16x32_bf16 v[74:77], v[160:163], v[208:211], v[74:77]
	v_mfma_f32_16x16x32_bf16 v[74:77], v[164:167], v[232:235], v[74:77]
	s_setprio 0
	s_setprio 1
	v_mfma_f32_16x16x32_bf16 v[118:121], v[168:171], v[184:187], v[118:121]
	v_mfma_f32_16x16x32_bf16 v[118:121], v[172:175], v[188:191], v[118:121]
	v_mfma_f32_16x16x32_bf16 v[102:105], v[168:171], v[192:195], v[102:105]
	v_mfma_f32_16x16x32_bf16 v[102:105], v[172:175], v[196:199], v[102:105]
	v_mfma_f32_16x16x32_bf16 v[86:89], v[168:171], v[200:203], v[86:89]
	v_mfma_f32_16x16x32_bf16 v[86:89], v[172:175], v[204:207], v[86:89]
	v_mfma_f32_16x16x32_bf16 v[70:73], v[168:171], v[208:211], v[70:73]
	v_mfma_f32_16x16x32_bf16 v[70:73], v[172:175], v[232:235], v[70:73]
	v_mfma_f32_16x16x32_bf16 v[114:117], v[176:179], v[184:187], v[114:117]
	v_mfma_f32_16x16x32_bf16 v[114:117], v[180:183], v[188:191], v[114:117]
	v_mfma_f32_16x16x32_bf16 v[98:101], v[176:179], v[192:195], v[98:101]
	v_mfma_f32_16x16x32_bf16 v[98:101], v[180:183], v[196:199], v[98:101]
	v_mfma_f32_16x16x32_bf16 v[82:85], v[176:179], v[200:203], v[82:85]
	v_mfma_f32_16x16x32_bf16 v[82:85], v[180:183], v[204:207], v[82:85]
	v_mfma_f32_16x16x32_bf16 v[66:69], v[176:179], v[208:211], v[66:69]
	v_mfma_f32_16x16x32_bf16 v[66:69], v[180:183], v[232:235], v[66:69]
	s_setprio 0
	s_barrier
	s_add_i32 s22, s24, s16
	v_lshl_add_u64 v[148:149], v[148:149], 0, s[62:63]
	s_mov_b32 m0, s22
	ds_read_b128 v[184:187], v154 offset:49152
	ds_read_b128 v[188:191], v154 offset:50176
	ds_read_b128 v[192:195], v154 offset:51200
	ds_read_b128 v[196:199], v154 offset:52224
	ds_read_b128 v[200:203], v154 offset:53248
	ds_read_b128 v[204:207], v154 offset:54272
	ds_read_b128 v[208:211], v154 offset:55296
	ds_read_b128 v[232:235], v154 offset:56320
	global_load_lds_dwordx4 v[148:149], off
	s_add_i32 m0, s22, 0x2000
	s_add_u32 s22, s48, 0x80080
	v_lshl_add_u64 v[148:149], v[212:213], 0, s[62:63]
	s_addc_u32 s23, s49, 0
	s_add_i32 s24, s25, s16
	global_load_lds_dwordx4 v[148:149], off
	v_lshl_add_u64 v[148:149], s[22:23], 0, v[134:135]
	s_mov_b32 m0, s24
	s_nop 0
	global_load_lds_dwordx4 v[148:149], off
	v_lshl_add_u64 v[148:149], s[22:23], 0, v[130:131]
	s_add_i32 m0, s24, 0x2000
	s_nop 0
	global_load_lds_dwordx4 v[148:149], off
	v_lshl_add_u64 v[148:149], v[236:237], 0, s[62:63]
	s_mov_b32 m0, s69
	s_nop 0
	global_load_lds_dwordx4 v[148:149], off
	v_lshl_add_u64 v[148:149], v[238:239], 0, s[62:63]
	s_mov_b32 m0, s70
	s_nop 0
	global_load_lds_dwordx4 v[148:149], off
	s_waitcnt vmcnt(8)
	s_waitcnt lgkmcnt(0)
	s_barrier
	s_setprio 1
	s_waitcnt lgkmcnt(0)
	v_mfma_f32_16x16x32_bf16 v[62:65], v[144:147], v[184:187], v[62:65]
	v_mfma_f32_16x16x32_bf16 v[62:65], v[156:159], v[188:191], v[62:65]
	v_mfma_f32_16x16x32_bf16 v[46:49], v[144:147], v[192:195], v[46:49]
	v_mfma_f32_16x16x32_bf16 v[46:49], v[156:159], v[196:199], v[46:49]
	v_mfma_f32_16x16x32_bf16 v[30:33], v[144:147], v[200:203], v[30:33]
	v_mfma_f32_16x16x32_bf16 v[30:33], v[156:159], v[204:207], v[30:33]
	v_mfma_f32_16x16x32_bf16 v[14:17], v[144:147], v[208:211], v[14:17]
	v_mfma_f32_16x16x32_bf16 v[14:17], v[156:159], v[232:235], v[14:17]
	v_mfma_f32_16x16x32_bf16 v[58:61], v[160:163], v[184:187], v[58:61]
	v_mfma_f32_16x16x32_bf16 v[58:61], v[164:167], v[188:191], v[58:61]
	v_mfma_f32_16x16x32_bf16 v[42:45], v[160:163], v[192:195], v[42:45]
	v_mfma_f32_16x16x32_bf16 v[42:45], v[164:167], v[196:199], v[42:45]
	v_mfma_f32_16x16x32_bf16 v[26:29], v[160:163], v[200:203], v[26:29]
	v_mfma_f32_16x16x32_bf16 v[26:29], v[164:167], v[204:207], v[26:29]
	v_mfma_f32_16x16x32_bf16 v[10:13], v[160:163], v[208:211], v[10:13]
	v_mfma_f32_16x16x32_bf16 v[10:13], v[164:167], v[232:235], v[10:13]
	s_setprio 0
	s_setprio 1
	v_mfma_f32_16x16x32_bf16 v[54:57], v[168:171], v[184:187], v[54:57]
	v_mfma_f32_16x16x32_bf16 v[54:57], v[172:175], v[188:191], v[54:57]
	v_mfma_f32_16x16x32_bf16 v[38:41], v[168:171], v[192:195], v[38:41]
	v_mfma_f32_16x16x32_bf16 v[38:41], v[172:175], v[196:199], v[38:41]
	v_mfma_f32_16x16x32_bf16 v[22:25], v[168:171], v[200:203], v[22:25]
	v_mfma_f32_16x16x32_bf16 v[22:25], v[172:175], v[204:207], v[22:25]
	v_mfma_f32_16x16x32_bf16 v[6:9], v[168:171], v[208:211], v[6:9]
	v_mfma_f32_16x16x32_bf16 v[6:9], v[172:175], v[232:235], v[6:9]
	v_mfma_f32_16x16x32_bf16 v[50:53], v[176:179], v[184:187], v[50:53]
	v_mfma_f32_16x16x32_bf16 v[50:53], v[180:183], v[188:191], v[50:53]
	v_mfma_f32_16x16x32_bf16 v[34:37], v[176:179], v[192:195], v[34:37]
	v_mfma_f32_16x16x32_bf16 v[34:37], v[180:183], v[196:199], v[34:37]
	v_mfma_f32_16x16x32_bf16 v[18:21], v[176:179], v[200:203], v[18:21]
	v_mfma_f32_16x16x32_bf16 v[18:21], v[180:183], v[204:207], v[18:21]
	v_mfma_f32_16x16x32_bf16 v[2:5], v[176:179], v[208:211], v[2:5]
	v_mfma_f32_16x16x32_bf16 v[2:5], v[180:183], v[232:235], v[2:5]
	s_setprio 0
	s_barrier
	s_add_i32 s21, s21, 2
	s_add_u32 s46, s46, 0x100
	s_addc_u32 s47, s47, 0
	s_add_u32 s19, s19, 0x100
	s_addc_u32 s20, s20, 0
	s_cmp_gt_u32 s21, 29
	s_cbranch_scc0 .LBB0_340
	s_and_b64 vcc, exec, s[8:9]
	s_cbranch_vccz .LBB0_343
	s_barrier
